# gridDim.x cached in a VGPR lane at kernel start instead of one scalar load per phase (on top of early-invalidate barrier and selective write-back)
# baseline (speedup 1.0000x reference)
.LBB0_7:
	s_mov_b64 s[4:5], s[12:13]
	v_writelane_b32 v252, s4, 2
	s_cmp_ge_i32 s12, s13
	s_nop 0
	v_writelane_b32 v252, s5, 3
	v_writelane_b32 v252, s6, 4
	v_writelane_b32 v252, s7, 5
	s_cbranch_scc1 .LBB0_1354
	s_load_dwordx4 s[84:87], s[0:1], 0xe0
	s_load_dwordx8 s[4:11], s[0:1], 0xc0
	s_add_u32 s2, s88, 0x10000
	s_addc_u32 s3, s89, 0
	v_mbcnt_lo_u32_b32 v2, -1, 0
	v_mbcnt_hi_u32_b32 v229, -1, v2
	s_waitcnt lgkmcnt(0)
	v_writelane_b32 v252, s4, 6
	v_and_b32_e32 v2, 64, v229
	v_mov_b32_e32 v3, 0
	v_writelane_b32 v252, s5, 7
	v_writelane_b32 v252, s6, 8
	v_writelane_b32 v252, s7, 9
	v_writelane_b32 v252, s8, 10
	v_writelane_b32 v252, s9, 11
	v_writelane_b32 v252, s10, 12
	v_writelane_b32 v252, s11, 13
	s_load_dwordx16 s[4:19], s[0:1], 0x0
	s_movk_i32 s95, 0x2000
	v_mov_b32_e32 v1, 0x358637bd
	s_mov_b32 s91, 0x800000
	s_mov_b64 s[82:83], 0x80
	s_waitcnt lgkmcnt(0)
	v_writelane_b32 v252, s4, 14
	s_mov_b32 s33, 0x3e16c740
	s_mov_b64 s[92:93], 0x200
	v_writelane_b32 v252, s5, 15
	v_writelane_b32 v252, s6, 16
	v_writelane_b32 v252, s7, 17
	v_writelane_b32 v252, s8, 18
	v_writelane_b32 v252, s9, 19
	v_writelane_b32 v252, s10, 20
	v_writelane_b32 v252, s11, 21
	v_writelane_b32 v252, s12, 22
	v_writelane_b32 v252, s13, 23
	v_writelane_b32 v252, s14, 24
	v_writelane_b32 v252, s15, 25
	v_writelane_b32 v252, s16, 26
	v_writelane_b32 v252, s17, 27
	v_writelane_b32 v252, s18, 28
	v_writelane_b32 v252, s19, 29
	s_load_dwordx16 s[4:19], s[0:1], 0x40
	s_mov_b64 s[80:81], 0x1200
	v_mov_b32_e32 v226, 0x22800
	v_mov_b32_e32 v227, 0x22804
	v_mov_b32_e32 v228, 1
	s_waitcnt lgkmcnt(0)
	v_writelane_b32 v252, s4, 30
	v_xor_b32_e32 v230, 16, v229
	v_add_u32_e32 v231, 64, v2
	v_writelane_b32 v252, s5, 31
	v_writelane_b32 v252, s6, 32
	v_writelane_b32 v252, s7, 33
	v_writelane_b32 v252, s8, 34
	v_writelane_b32 v252, s9, 35
	v_writelane_b32 v252, s10, 36
	v_writelane_b32 v252, s11, 37
	v_writelane_b32 v252, s12, 38
	v_writelane_b32 v252, s13, 39
	v_writelane_b32 v252, s14, 40
	v_writelane_b32 v252, s15, 41
	v_writelane_b32 v252, s16, 42
	v_writelane_b32 v252, s17, 43
	v_writelane_b32 v252, s18, 44
	v_writelane_b32 v252, s19, 45
	s_load_dwordx16 s[4:19], s[0:1], 0x80
	v_mov_b64_e32 v[180:181], 0x100
	v_mov_b64_e32 v[182:183], 0xff
	v_mov_b32_e32 v232, 0x1000
	v_mov_b32_e32 v233, 0x100
	s_waitcnt lgkmcnt(0)
	v_writelane_b32 v252, s4, 46
	v_mov_b32_e32 v234, 0x20000
	v_mov_b64_e32 v[184:185], 0x57f
	v_writelane_b32 v252, s5, 47
	v_writelane_b32 v252, s6, 48
	v_writelane_b32 v252, s7, 49
	v_writelane_b32 v252, s8, 50
	v_writelane_b32 v252, s9, 51
	v_writelane_b32 v252, s10, 52
	v_writelane_b32 v252, s11, 53
	v_writelane_b32 v252, s12, 54
	v_writelane_b32 v252, s13, 55
	v_writelane_b32 v252, s14, 56
	v_writelane_b32 v252, s15, 57
	v_writelane_b32 v252, s16, 58
	v_writelane_b32 v252, s17, 59
	v_writelane_b32 v252, s18, 60
	v_writelane_b32 v252, s19, 61
	v_writelane_b32 v252, s2, 62
	v_mov_b64_e32 v[186:187], 0x580
	v_mov_b32_e32 v188, 0x22808
	v_writelane_b32 v252, s3, 63
	s_add_u32 s2, s88, 0x4000
	v_writelane_b32 v253, s2, 0
	s_addc_u32 s2, s89, 0
	s_add_u32 s0, s0, 0x108
	v_writelane_b32 v253, s2, 1
	s_addc_u32 s1, s1, 0
	v_writelane_b32 v253, s0, 2
	v_mov_b32_e32 v235, 0x70
	v_mov_b32_e32 v236, 0x42800000
	v_writelane_b32 v253, s1, 3
	s_load_dword s98, s[0:1], 0x0
	s_waitcnt lgkmcnt(0)
	v_writelane_b32 v254, s98, 2
	s_lshl_b32 s0, s90, 3
	s_add_u32 s10, s88, 0x6198000
	s_addc_u32 s11, s89, 0
	v_writelane_b32 v253, s0, 4
	s_add_u32 s0, s88, 0x14340000
	s_addc_u32 s1, s89, 0
	v_writelane_b32 v253, s0, 5
	v_not_b32_e32 v237, 63
	v_mov_b32_e32 v238, 0x200
	v_writelane_b32 v253, s1, 6
	s_lshl_b32 s0, s90, 9
	s_cmpk_lt_i32 s90, 0x5cc
	v_writelane_b32 v253, s0, 7
	s_cselect_b64 s[0:1], -1, 0
	v_writelane_b32 v253, s0, 8
	v_mov_b64_e32 v[190:191], 0x23f
	v_mov_b64_e32 v[192:193], 0x240
	v_writelane_b32 v253, s1, 9
	s_add_u32 s0, s88, 0x6118000
	v_writelane_b32 v253, s0, 10
	s_addc_u32 s0, s89, 0
	v_writelane_b32 v253, s0, 11
	s_add_u32 s0, s88, 0x5f18000
	v_writelane_b32 v253, s0, 12
	s_addc_u32 s0, s89, 0
	v_writelane_b32 v253, s0, 13
	s_add_u32 s0, s88, 0x4798000
	s_addc_u32 s1, s89, 0
	v_writelane_b32 v253, s0, 14
	s_nop 1
	v_writelane_b32 v253, s1, 15
	s_add_u32 s0, s88, 0x1b98000
	s_addc_u32 s1, s89, 0
	v_writelane_b32 v253, s0, 16
	s_nop 1
	v_writelane_b32 v253, s1, 17
	s_add_u32 s0, s88, 0x1398000
	s_addc_u32 s1, s89, 0
	v_writelane_b32 v253, s0, 18
	s_nop 1
	v_writelane_b32 v253, s1, 19
	s_add_u32 s0, s88, 0x1318000
	s_addc_u32 s1, s89, 0
	v_writelane_b32 v253, s0, 20
	s_nop 1
	v_writelane_b32 v253, s1, 21
	s_add_u32 s0, s88, 0x1258000
	s_addc_u32 s1, s89, 0
	v_writelane_b32 v253, s0, 22
	s_nop 1
	v_writelane_b32 v253, s1, 23
	s_add_u32 s0, s88, 0x58000
	s_addc_u32 s1, s89, 0
	s_add_u32 s12, s88, 0x8198000
	v_writelane_b32 v253, s0, 24
	s_addc_u32 s13, s89, 0
	s_nop 0
	v_writelane_b32 v253, s1, 25
	s_add_u32 s0, s88, 0x12340000
	s_addc_u32 s1, s89, 0
	v_writelane_b32 v253, s0, 26
	s_cmpk_lt_i32 s90, 0x100
	s_nop 0
	v_writelane_b32 v253, s1, 27
	s_cselect_b64 s[0:1], -1, 0
	v_writelane_b32 v253, s0, 28
	s_nop 1
	v_writelane_b32 v253, s1, 29
	s_ashr_i32 s0, s90, 31
	v_writelane_b32 v253, s0, 30
	s_lshr_b32 s0, s0, 29
	s_add_i32 s0, s90, s0
	s_ashr_i32 s6, s0, 3
	s_and_b32 s0, s0, -8
	s_sub_i32 s2, s90, s0
	s_lshl_b32 s0, s2, 5
	s_add_u32 s4, s88, 0x14580000
	s_addc_u32 s5, s89, 0
	v_writelane_b32 v253, s4, 31
	s_cmpk_lt_i32 s90, 0x580
	s_mul_i32 s3, s2, 33
	v_writelane_b32 v253, s5, 32
	s_cselect_b64 s[4:5], -1, 0
	v_writelane_b32 v253, s4, 33
	s_cmp_lt_i32 s2, 0
	s_cselect_b32 s7, s3, s0
	v_writelane_b32 v253, s5, 34
	s_movk_i32 s4, 0xb1
	s_cselect_b32 s4, s4, 0xb0
	s_mul_i32 s4, s4, s2
	s_movk_i32 s5, 0x49
	s_cselect_b32 s5, s5, 0x48
	s_add_i32 s4, s4, s6
	s_mul_hi_i32 s0, s4, 0x2e8ba2e9
	s_lshr_b32 s3, s0, 31
	s_ashr_i32 s0, s0, 5
	s_add_i32 s0, s0, s3
	s_mul_i32 s3, s0, 0xb0
	s_sub_i32 s3, s4, s3
	s_lshl_b32 s8, s0, 3
	s_bfe_u32 s0, s3, 0x3001c
	s_add_i32 s4, s3, s0
	s_sext_i32_i16 s9, s4
	s_and_b32 s4, s4, 0xfff8
	s_sub_i32 s3, s3, s4
	s_sext_i32_i16 s3, s3
	s_lshr_b32 s0, s9, 3
	s_add_i32 s14, s8, s3
	s_ashr_i32 s3, s9, 3
	s_add_u32 s9, s88, 0x10340000
	s_addc_u32 s16, s89, 0
	s_add_u32 s18, s88, 0x14b00000
	v_writelane_b32 v253, s3, 35
	s_addc_u32 s19, s89, 0
	v_writelane_b32 v253, s18, 36
	s_mul_i32 s2, s5, s2
	s_mov_b32 s1, 0
	v_writelane_b32 v253, s19, 37
	s_add_u32 s18, s88, 0x15300000
	s_addc_u32 s19, s89, 0
	v_writelane_b32 v253, s18, 38
	s_nop 1
	v_writelane_b32 v253, s19, 39
	s_add_u32 s18, s88, 0xc998000
	s_addc_u32 s19, s89, 0
	v_writelane_b32 v253, s18, 40
	s_nop 1
	v_writelane_b32 v253, s19, 41
	s_add_u32 s18, s88, 0xe6c0000
	s_addc_u32 s19, s89, 0
	v_writelane_b32 v253, s18, 42
	s_nop 1
	v_writelane_b32 v253, s19, 43
	s_add_u32 s18, s88, 0xf2c0000
	s_addc_u32 s19, s89, 0
	v_writelane_b32 v253, s18, 44
	s_nop 1
	v_writelane_b32 v253, s19, 45
	s_add_u32 s18, s88, 0xfb00000
	s_addc_u32 s19, s89, 0
	v_writelane_b32 v253, s18, 46
	s_nop 1
	v_writelane_b32 v253, s19, 47
	s_add_u32 s18, s88, 0xe5b8000
	s_addc_u32 s19, s89, 0
	v_writelane_b32 v253, s18, 48
	s_add_u32 s3, s88, 0x5d98000
	s_nop 0
	v_writelane_b32 v253, s19, 49
	v_cmp_eq_u32_e64 s[18:19], 0, v0
	s_nop 1
	v_writelane_b32 v253, s18, 50
	s_nop 1
	v_writelane_b32 v253, s19, 51
	v_writelane_b32 v253, s3, 52
	s_addc_u32 s3, s89, 0
	v_writelane_b32 v253, s3, 53
	s_add_u32 s3, s88, 0x6098000
	v_writelane_b32 v253, s3, 54
	s_addc_u32 s3, s89, 0
	s_add_u32 s18, s88, 0xd998000
	v_writelane_b32 v253, s3, 55
	s_addc_u32 s19, s89, 0
	v_writelane_b32 v253, s18, 56
	s_nop 1
	v_writelane_b32 v253, s19, 57
	s_add_u32 s18, s88, 0xe198000
	s_addc_u32 s19, s89, 0
	v_writelane_b32 v253, s18, 58
	s_cmpk_lt_i32 s90, 0x200
	s_nop 0
	v_writelane_b32 v253, s19, 59
	s_cselect_b64 s[18:19], -1, 0
	v_writelane_b32 v253, s18, 60
	s_cmpk_lt_i32 s90, 0x240
	s_nop 0
	v_writelane_b32 v253, s19, 61
	s_cselect_b64 s[18:19], -1, 0
	s_add_i32 s2, s2, s6
	s_mul_hi_i32 s3, s2, 0x38e38e39
	s_lshr_b32 s4, s3, 31
	s_ashr_i32 s3, s3, 4
	s_add_i32 s3, s3, s4
	s_mul_i32 s4, s3, 0x48
	s_sub_i32 s4, s2, s4
	s_bfe_i32 s2, s4, 0x80000
	s_bfe_u32 s2, s2, 0x3000c
	s_add_i32 s5, s4, s2
	s_bfe_i32 s2, s5, 0x80000
	s_and_b32 s5, s5, 0xf8
	s_sub_i32 s4, s4, s5
	v_writelane_b32 v253, s18, 62
	s_lshl_b32 s3, s3, 3
	s_sext_i32_i16 s8, s2
	s_sext_i32_i8 s4, s4
	v_writelane_b32 v253, s19, 63
	s_add_i32 s18, s3, s4
	s_ashr_i32 s3, s8, 3
	s_lshr_b32 s2, s8, 3
	v_writelane_b32 v251, s3, 0
	s_mov_b32 s4, s18
	v_writelane_b32 v251, s4, 1
	s_bfe_i64 s[2:3], s[2:3], 0x100000
	s_ashr_i32 s19, s18, 31
	v_writelane_b32 v251, s5, 2
	s_lshl_b64 s[2:3], s[2:3], 19
	s_lshl_b64 s[4:5], s[18:19], 19
	v_writelane_b32 v251, s2, 3
	s_nop 1
	v_writelane_b32 v251, s3, 4
	s_add_u32 s2, s10, s4
	s_addc_u32 s3, s11, s5
	s_add_u32 s4, s2, 0x40000
	v_writelane_b32 v251, s2, 5
	s_addc_u32 s5, s3, 0
	s_cmpk_lt_i32 s90, 0x2ec
	v_writelane_b32 v251, s3, 6
	v_writelane_b32 v251, s4, 7
	s_cselect_b64 s[2:3], -1, 0
	s_nop 0
	v_writelane_b32 v251, s5, 8
	v_writelane_b32 v251, s2, 9
	s_nop 1
	v_writelane_b32 v251, s3, 10
	s_add_i32 s2, s7, s6
	s_ashr_i32 s3, s2, 31
	s_lshr_b32 s3, s3, 27
	s_add_i32 s3, s2, s3
	s_ashr_i32 s4, s3, 5
	s_and_b32 s3, s3, 0xffe0
	s_sub_i32 s3, s2, s3
	s_bfe_i32 s2, s3, 0x80000
	s_bfe_u32 s2, s2, 0x3000c
	s_add_i32 s5, s3, s2
	s_bfe_i32 s2, s5, 0x80000
	s_and_b32 s5, s5, 0xf8
	s_sub_i32 s3, s3, s5
	s_lshl_b32 s4, s4, 3
	s_sext_i32_i16 s6, s2
	s_sext_i32_i8 s3, s3
	s_lshr_b32 s2, s6, 3
	s_add_i32 s18, s4, s3
	s_ashr_i32 s3, s6, 3
	v_writelane_b32 v251, s3, 11
	s_ashr_i32 s19, s18, 31
	s_mul_i32 s5, s18, 0x160000
	s_bfe_i64 s[2:3], s[2:3], 0x100000
	s_mul_hi_i32 s4, s18, 0x160000
	s_add_u32 s6, s12, s5
	v_writelane_b32 v251, s12, 12
	s_addc_u32 s7, s13, s4
	s_add_u32 s4, s6, 0xb0000
	v_writelane_b32 v251, s13, 13
	v_writelane_b32 v251, s6, 14
	s_addc_u32 s5, s7, 0
	s_ashr_i32 s15, s14, 31
	v_writelane_b32 v251, s7, 15
	v_writelane_b32 v251, s4, 16
	s_bfe_i64 s[6:7], s[0:1], 0x100000
	s_lshl_b64 s[6:7], s[6:7], 19
	v_writelane_b32 v251, s5, 17
	s_mov_b32 s4, s14
	v_writelane_b32 v251, s4, 18
	s_mov_b32 s0, s18
	s_nop 0
	v_writelane_b32 v251, s5, 19
	v_writelane_b32 v251, s6, 20
	s_lshl_b64 s[4:5], s[14:15], 19
	s_add_u32 s4, s10, s4
	v_writelane_b32 v251, s7, 21
	v_writelane_b32 v251, s10, 22
	s_addc_u32 s5, s11, s5
	s_add_u32 s6, s4, 0x40000
	v_writelane_b32 v251, s11, 23
	v_writelane_b32 v251, s4, 24
	s_addc_u32 s7, s5, 0
	s_lshl_b64 s[2:3], s[2:3], 19
	v_writelane_b32 v251, s5, 25
	v_writelane_b32 v251, s6, 26
	s_lshl_b64 s[4:5], s[18:19], 19
	s_nop 0
	v_writelane_b32 v251, s7, 27
	v_writelane_b32 v251, s0, 28
	s_nop 1
	v_writelane_b32 v251, s1, 29
	v_writelane_b32 v251, s2, 30
	s_nop 1
	v_writelane_b32 v251, s3, 31
	v_writelane_b32 v251, s9, 32
	s_add_u32 s2, s9, s4
	v_writelane_b32 v251, s16, 33
	s_addc_u32 s3, s16, s5
	s_add_u32 s4, s2, 0x40000
	v_writelane_b32 v251, s2, 34
	s_addc_u32 s5, s3, 0
	s_lshl_b32 s0, s90, 11
	v_writelane_b32 v251, s3, 35
	v_writelane_b32 v251, s4, 36
	s_nop 1
	v_writelane_b32 v251, s5, 37
	v_writelane_b32 v251, s0, 38
	s_lshl_b32 s0, s90, 8
	v_writelane_b32 v251, s0, 39
	s_lshl_b32 s0, s90, 4
	v_writelane_b32 v251, s0, 40
	s_lshl_b32 s0, s90, 5
	v_writelane_b32 v251, s0, 41
	s_branch .LBB0_12

.LBB0_19:
	s_or_b64 exec, exec, s[6:7]
	s_and_saveexec_b64 s[2:3], vcc
	s_cbranch_execz .LBB0_29
	v_readlane_b32 s8, v252, 30
	v_lshlrev_b64 v[4:5], 2, v[88:89]
	v_readlane_b32 s16, v252, 38
	v_readlane_b32 s17, v252, 39
	v_readlane_b32 s6, v253, 2
	v_readlane_b32 s7, v253, 3
	v_lshl_add_u64 v[26:27], s[16:17], 0, v[4:5]
	global_load_dwordx4 v[14:17], v[26:27], off offset:3072
	global_load_dwordx4 v[18:21], v[26:27], off offset:2048
	global_load_dwordx4 v[22:25], v[26:27], off offset:1024
	s_nop 0
	global_load_dwordx4 v[26:29], v[26:27], off
	v_readlane_b32 s0, v254, 2
	v_readlane_b32 s9, v252, 31
	v_cmp_lt_i32_e32 vcc, v230, v231
	v_lshlrev_b64 v[40:41], 11, v[86:87]
	v_readlane_b32 s8, v251, 22
	s_waitcnt lgkmcnt(0)
	s_lshl_b32 s6, s0, 3
	v_readlane_b32 s0, v253, 4
	s_add_i32 s0, s0, s6
	v_cndmask_b32_e32 v2, v229, v230, vcc
	v_add_u32_e32 v92, s0, v38
	v_lshlrev_b64 v[38:39], 12, v[86:87]
	v_lshl_add_u64 v[4:5], v[38:39], 0, v[4:5]
	v_lshl_add_u64 v[40:41], v[88:89], 1, v[40:41]
	v_readlane_b32 s9, v251, 23
	v_lshl_add_u64 v[94:95], s[86:87], 0, v[4:5]
	v_mov_b32_e32 v4, v3
	v_mov_b32_e32 v5, v3
	v_readlane_b32 s10, v252, 32
	v_readlane_b32 s11, v252, 33
	v_readlane_b32 s12, v252, 34
	v_readlane_b32 s13, v252, 35
	v_lshlrev_b32_e32 v96, 2, v2
	v_lshl_add_u64 v[90:91], s[8:9], 0, v[40:41]
	s_ashr_i32 s7, s6, 31
	v_mov_b32_e32 v2, v3
	v_mov_b64_e32 v[64:65], v[4:5]
	v_mov_b64_e32 v[68:69], v[4:5]
	v_mov_b64_e32 v[80:81], v[4:5]
	v_mov_b64_e32 v[84:85], v[4:5]
	v_mov_b64_e32 v[48:49], v[4:5]
	v_mov_b64_e32 v[40:41], v[4:5]
	v_mov_b64_e32 v[44:45], v[4:5]
	v_mov_b64_e32 v[56:57], v[4:5]
	v_mov_b64_e32 v[72:73], v[4:5]
	v_mov_b64_e32 v[76:77], v[4:5]
	v_mov_b64_e32 v[60:61], v[4:5]
	v_mov_b64_e32 v[52:53], v[4:5]
	v_mov_b32_e32 v97, -1
	s_lshl_b64 s[8:9], s[6:7], 11
	v_ashrrev_i32_e32 v93, 31, v92
	s_lshl_b64 s[10:11], s[6:7], 12
	s_mov_b64 s[12:13], 0
	v_mov_b64_e32 v[62:63], v[2:3]
	v_mov_b64_e32 v[66:67], v[2:3]
	v_mov_b64_e32 v[78:79], v[2:3]
	v_mov_b64_e32 v[82:83], v[2:3]
	v_mov_b64_e32 v[46:47], v[2:3]
	v_mov_b64_e32 v[38:39], v[2:3]
	v_mov_b64_e32 v[42:43], v[2:3]
	v_mov_b64_e32 v[54:55], v[2:3]
	v_mov_b64_e32 v[70:71], v[2:3]
	v_mov_b64_e32 v[74:75], v[2:3]
	v_mov_b64_e32 v[58:59], v[2:3]
	v_mov_b64_e32 v[50:51], v[2:3]
	v_readlane_b32 s14, v252, 36
	v_readlane_b32 s15, v252, 37
	v_readlane_b32 s18, v252, 40
	v_readlane_b32 s19, v252, 41
	v_readlane_b32 s20, v252, 42
	v_readlane_b32 s21, v252, 43
	v_readlane_b32 s22, v252, 44
	v_readlane_b32 s23, v252, 45
	s_branch .LBB0_22

.LBB0_31:
	s_and_b64 vcc, exec, s[6:7]
	s_cbranch_vccz .LBB0_36
	v_mov_b32_e32 v2, v0
	v_readlane_b32 s0, v253, 7
	v_and_b32_e32 v2, 0x1ff, v2
	s_nop 0
	v_or_b32_e32 v4, s0, v2
	s_mov_b32 s0, 0x12000
	v_cmp_gt_i32_e32 vcc, s0, v4
	s_and_saveexec_b64 s[6:7], vcc
	v_readlane_b32 s12, v252, 30
	v_readlane_b32 s13, v252, 31
	v_readlane_b32 s14, v252, 32
	v_readlane_b32 s15, v252, 33
	v_readlane_b32 s16, v252, 34
	v_readlane_b32 s12, v252, 62
	v_readlane_b32 s14, v253, 5
	v_readlane_b32 s18, v252, 36
	v_readlane_b32 s19, v252, 37
	v_readlane_b32 s13, v252, 63
	v_readlane_b32 s15, v253, 6
	s_mov_b32 s11, 0x2aaaaaab
	s_mov_b32 s16, 0x48000
	v_readlane_b32 s17, v252, 35
	v_readlane_b32 s20, v252, 38
	v_readlane_b32 s21, v252, 39
	v_readlane_b32 s22, v252, 40
	v_readlane_b32 s23, v252, 41
	v_readlane_b32 s24, v252, 42
	v_readlane_b32 s25, v252, 43
	v_readlane_b32 s26, v252, 44
	v_readlane_b32 s27, v252, 45
	s_cbranch_execz .LBB0_35
	v_readlane_b32 s8, v253, 2
	v_readlane_b32 s9, v253, 3
	v_readlane_b32 s0, v254, 2
	s_mov_b64 s[8:9], 0
	s_waitcnt lgkmcnt(0)
	s_lshl_b32 s0, s0, 9

.LBB0_38:
	v_readlane_b32 s4, v252, 2
	s_add_i32 s0, s4, -3
	s_mul_hi_i32 s2, s0, 0x2e8ba2e9
	s_lshr_b32 s3, s2, 31
	s_ashr_i32 s2, s2, 1
	s_add_i32 s4, s2, s3
	s_mul_i32 s2, s4, 11
	s_sub_i32 s34, s0, s2
	s_mov_b32 s2, s4
	v_readlane_b32 s5, v252, 3
	v_writelane_b32 v251, s2, 42
	s_mul_i32 s0, s4, 3
	s_mul_hi_i32 s0, s0, 0x6000
	v_writelane_b32 v251, s3, 43
	s_mul_i32 s2, s4, 0x12000
	v_readlane_b32 s4, v252, 62
	v_readlane_b32 s5, v252, 63
	s_add_u32 s2, s4, s2
	s_addc_u32 s3, s5, s0
	v_writelane_b32 v251, s2, 44
	s_mov_b64 s[4:5], 0
	s_mov_b64 s[48:49], 0
	v_writelane_b32 v251, s3, 45
	v_writelane_b32 v251, s4, 46
	s_mov_b64 s[2:3], -1
	s_cmp_lt_i32 s34, 5
	v_writelane_b32 v251, s5, 47
	v_readlane_b32 s6, v252, 4
	v_readlane_b32 s7, v252, 5
	v_writelane_b32 v251, s34, 48
	s_cbranch_scc1 .LBB0_298
	s_cmp_gt_i32 s34, 6
	s_cbranch_scc0 .LBB0_65
	s_cmp_gt_i32 s34, 7
	s_cbranch_scc0 .LBB0_66
	s_cmp_gt_i32 s34, 8
	s_cbranch_scc0 .LBB0_67
	s_cmp_eq_u32 s34, 9
	s_cbranch_scc0 .LBB0_64
	s_waitcnt vmcnt(0)
	v_mov_b32_e32 v9, v0
	v_readlane_b32 s2, v253, 28
	v_readlane_b32 s3, v253, 29
	v_and_b32_e32 v2, 0x1ff, v9
	s_andn2_b64 vcc, exec, s[2:3]
	v_readfirstlane_b32 s0, v2
	s_cbranch_vccnz .LBB0_63
	v_readlane_b32 s2, v251, 42
	v_lshrrev_b32_e32 v4, 5, v9
	v_readlane_b32 s3, v251, 43
	s_mov_b32 s4, s2
	v_and_b32_e32 v5, 4, v4
	v_lshrrev_b32_e32 v4, 1, v9
	s_mul_i32 s3, s4, 0x580000
	v_readlane_b32 s4, v253, 14
	v_bfe_u32 v6, v9, 2, 2
	v_and_b32_e32 v4, 24, v4
	v_lshrrev_b32_e32 v10, 3, v2
	s_add_u32 s14, s4, s3
	v_or3_b32 v8, v5, v6, v4
	v_or_b32_e32 v7, 64, v10
	s_movk_i32 s4, 0x60
	v_and_or_b32 v5, v7, s4, v8
	v_mul_u32_u24_e32 v11, 0xb00, v5
	v_lshlrev_b32_e32 v2, 4, v2
	v_and_b32_e32 v5, 32, v9
	v_bitop3_b32 v5, v2, v5, 48 bitop3:0x6c
	v_and_b32_e32 v6, 64, v9
	v_or_b32_e32 v2, v5, v6
	v_lshrrev_b32_e32 v12, 1, v2
	v_or_b32_e32 v2, v11, v12
	v_bfe_u32 v11, v9, 2, 4
	s_movk_i32 s4, 0x70
	v_lshlrev_b32_e32 v132, 1, v2
	v_and_or_b32 v2, v7, s4, v11
	s_mul_hi_i32 s2, s2, 0x580000
	v_readlane_b32 s5, v253, 15
	v_mul_u32_u24_e32 v7, 0xb00, v2
	s_addc_u32 s15, s5, s2
	s_lshr_b32 s2, s0, 6
	v_or_b32_e32 v2, v7, v12
	v_readlane_b32 s5, v251, 11
	s_lshr_b32 s3, s0, 8
	s_lshl_b32 s16, s2, 10
	v_lshlrev_b32_e32 v134, 1, v2
	v_and_or_b32 v2, v10, 32, v8
	s_mul_i32 s4, s5, 0x160000
	v_mul_u32_u24_e32 v2, 0xb00, v2
	s_add_u32 s10, s14, s4
	s_mul_hi_i32 s4, s5, 0x160000
	v_or_b32_e32 v2, v2, v12
	v_and_or_b32 v8, v10, 48, v11
	s_addc_u32 s11, s15, s4
	s_add_i32 s17, s16, 0x10000
	v_lshlrev_b32_e32 v2, 1, v2
	v_mul_u32_u24_e32 v8, 0xb00, v8
	s_mov_b32 m0, s17
	s_add_i32 s18, s16, 0x12000
	v_or_b32_e32 v10, v12, v8
	global_load_lds_dwordx4 v2, s[10:11]
	s_mov_b32 m0, s18
	v_readlane_b32 s4, v251, 14
	v_lshlrev_b32_e32 v136, 1, v10
	global_load_lds_dwordx4 v132, s[10:11]
	s_mov_b32 m0, s16
	v_readlane_b32 s5, v251, 15
	s_add_i32 s19, s16, 0x2000
	s_nop 3
	global_load_lds_dwordx4 v136, s[4:5]
	s_mov_b32 m0, s19
	s_nop 0
	global_load_lds_dwordx4 v134, s[4:5]
	s_add_u32 s4, s10, 0xb0000
	s_addc_u32 s5, s11, 0
	s_add_i32 s20, s16, 0x14000
	s_mov_b32 m0, s20
	s_add_i32 s21, s16, 0x16000
	global_load_lds_dwordx4 v2, s[4:5]
	s_mov_b32 m0, s21
	s_add_i32 s22, s16, 0x4000
	global_load_lds_dwordx4 v132, s[4:5]
	v_readlane_b32 s4, v251, 16
	s_mov_b32 m0, s22
	v_readlane_b32 s5, v251, 17
	s_add_i32 s23, s16, 0x6000
	s_cmp_lg_u32 s3, 1
	s_nop 2
	global_load_lds_dwordx4 v136, s[4:5]
	s_mov_b32 m0, s23
	s_nop 0
	global_load_lds_dwordx4 v134, s[4:5]
	v_readlane_b32 s4, v253, 2
	v_readlane_b32 s5, v253, 3
	v_readlane_b32 s24, v254, 2
	s_cbranch_scc1 .LBB0_46
	s_barrier

.LBB0_67:
	s_mov_b64 s[4:5], 0
	v_writelane_b32 v251, s4, 46
	s_nop 1
	v_writelane_b32 v251, s5, 47
	s_and_b64 vcc, exec, s[2:3]
	s_cbranch_vccz .LBB0_86
	v_mov_b32_e32 v2, v0
	v_readlane_b32 s0, v253, 7
	v_and_b32_e32 v2, 0x1ff, v2
	s_waitcnt vmcnt(0)
	v_or_b32_e32 v16, s0, v2
	s_mov_b32 s0, 0x58000
	v_cmp_gt_i32_e32 vcc, s0, v16
	s_and_saveexec_b64 s[4:5], vcc
	s_cbranch_execz .LBB0_85
	v_readlane_b32 s2, v251, 42
	v_readlane_b32 s8, v252, 6
	v_readlane_b32 s3, v251, 43
	s_mov_b32 s16, s2
	s_mul_hi_i32 s0, s2, 0x10800
	s_mul_i32 s2, s2, 0x10800
	v_readlane_b32 s12, v252, 10
	s_add_u32 s6, s12, s2
	v_readlane_b32 s2, v253, 2
	v_readlane_b32 s3, v253, 3
	v_readlane_b32 s2, v254, 2
	v_readlane_b32 s13, v252, 11
	v_readlane_b32 s14, v252, 12
	s_addc_u32 s7, s13, s0
	s_mul_i32 s3, s16, 0x5800
	v_readlane_b32 s9, v252, 7
	v_readlane_b32 s10, v252, 8
	v_readlane_b32 s11, v252, 9
	v_readlane_b32 s15, v252, 13
	s_mul_hi_i32 s0, s16, 0x5800
	s_add_u32 s8, s14, s3
	s_addc_u32 s9, s15, s0
	s_waitcnt lgkmcnt(0)
	s_lshl_b32 s0, s2, 9
	v_lshlrev_b32_e32 v17, 1, v16
	s_lshl_b32 s16, s2, 10
	s_mov_b64 s[10:11], 0
	s_branch .LBB0_72

.LBB0_87:
	s_waitcnt vmcnt(0)
	v_mov_b32_e32 v12, v0
	v_readlane_b32 s2, v253, 33
	v_readlane_b32 s3, v253, 34
	v_and_b32_e32 v2, 0x1ff, v12
	s_andn2_b64 vcc, exec, s[2:3]
	v_readfirstlane_b32 s2, v2
	s_cbranch_vccnz .LBB0_266
	v_readlane_b32 s4, v251, 42
	v_readlane_b32 s5, v251, 43
	s_mul_hi_i32 s0, s4, 0xb00000
	s_mul_i32 s3, s4, 0xb00000
	v_readlane_b32 s4, v253, 16
	v_readlane_b32 s5, v253, 17
	s_add_u32 s49, s4, s3
	s_addc_u32 s5, s5, s0
	s_lshr_b32 s4, s2, 6
	v_lshrrev_b32_e32 v4, 5, v12
	v_lshrrev_b32_e32 v6, 1, v12
	s_lshr_b32 s3, s2, 8
	s_lshl_b32 s96, s4, 10
	v_and_b32_e32 v4, 4, v4
	v_bfe_u32 v5, v12, 2, 2
	v_and_b32_e32 v6, 24, v6
	v_lshrrev_b32_e32 v8, 3, v2
	v_lshlrev_b32_e32 v7, 4, v2
	v_and_b32_e32 v9, 32, v12
	v_readlane_b32 s6, v251, 20
	v_or3_b32 v4, v4, v5, v6
	v_or_b32_e32 v5, 64, v8
	s_movk_i32 s0, 0x60
	v_bitop3_b32 v9, v7, v9, 48 bitop3:0x6c
	v_and_b32_e32 v10, 64, v12
	v_readlane_b32 s7, v251, 21
	s_add_u32 s6, s49, s6
	v_and_or_b32 v6, v5, s0, v4
	v_or_b32_e32 v7, v9, v10
	v_bfe_u32 v11, v12, 2, 4
	s_movk_i32 s0, 0x70
	v_and_or_b32 v4, v8, 32, v4
	s_addc_u32 s7, s5, s7
	s_add_i32 s97, s96, 0x10000
	v_and_or_b32 v5, v5, s0, v11
	v_lshl_or_b32 v198, v4, 11, v7
	v_writelane_b32 v251, s5, 60
	s_mov_b32 m0, s97
	s_add_i32 s0, s96, 0x12000
	v_lshl_or_b32 v194, v6, 11, v7
	v_and_or_b32 v4, v8, 48, v11
	global_load_lds_dwordx4 v198, s[6:7]
	s_mov_b32 m0, s0
	v_readlane_b32 s8, v251, 24
	v_lshl_or_b32 v200, v4, 11, v7
	global_load_lds_dwordx4 v194, s[6:7]
	s_mov_b32 m0, s96
	v_readlane_b32 s9, v251, 25
	s_add_i32 s48, s96, 0x2000
	v_lshl_or_b32 v196, v5, 11, v7
	v_mov_b32_e32 v199, v3
	v_mov_b32_e32 v195, v3
	v_lshl_add_u64 v[4:5], s[6:7], 0, v[198:199]
	global_load_lds_dwordx4 v200, s[8:9]
	s_mov_b32 m0, s48
	v_lshl_add_u64 v[6:7], s[6:7], 0, v[194:195]
	global_load_lds_dwordx4 v196, s[8:9]
	s_add_u32 s8, s6, 0x40000
	s_addc_u32 s9, s7, 0
	s_add_i32 s58, s96, 0x14000
	s_mov_b32 m0, s58
	s_add_i32 s59, s96, 0x16000
	global_load_lds_dwordx4 v198, s[8:9]
	s_mov_b32 m0, s59
	s_add_i32 s52, s96, 0x4000
	global_load_lds_dwordx4 v194, s[8:9]
	v_readlane_b32 s8, v251, 26
	s_mov_b32 m0, s52
	v_readlane_b32 s9, v251, 27
	s_add_i32 s53, s96, 0x6000
	s_cmp_eq_u32 s3, 1
	s_nop 2
	global_load_lds_dwordx4 v200, s[8:9]
	s_mov_b32 m0, s53
	s_nop 0
	global_load_lds_dwordx4 v196, s[8:9]
	v_readlane_b32 s8, v253, 2
	v_readlane_b32 s9, v253, 3
	v_readlane_b32 s5, v254, 2
	s_cselect_b64 s[8:9], -1, 0
	s_cmp_lg_u32 s3, 1
	s_waitcnt lgkmcnt(0)
	v_writelane_b32 v251, s5, 49
	v_writelane_b32 v251, s8, 61
	s_nop 1
	v_writelane_b32 v251, s9, 62
	s_cbranch_scc1 .LBB0_90
	s_barrier

.LBB0_272:
	s_or_b64 exec, exec, s[2:3]
	s_and_saveexec_b64 s[4:5], vcc
	s_cbranch_execz .LBB0_279
	v_readlane_b32 s2, v251, 42
	v_readlane_b32 s3, v251, 43
	s_lshl_b32 s2, s2, 10
	s_ashr_i32 s3, s2, 31
	v_readlane_b32 s8, v252, 30
	s_lshl_b64 s[2:3], s[2:3], 2
	v_readlane_b32 s18, v252, 40
	v_readlane_b32 s9, v252, 31
	v_readlane_b32 s19, v252, 41
	s_add_u32 s8, s18, s2
	v_readlane_b32 s20, v252, 42
	s_addc_u32 s9, s19, s3
	v_readlane_b32 s21, v252, 43
	s_add_u32 s2, s20, s2
	s_addc_u32 s3, s21, s3
	v_readlane_b32 s6, v253, 2
	v_lshlrev_b64 v[120:121], 2, v[118:119]
	v_readlane_b32 s7, v253, 3
	v_lshl_add_u64 v[4:5], s[2:3], 0, v[120:121]
	v_lshl_add_u64 v[34:35], s[8:9], 0, v[120:121]
	v_readlane_b32 s0, v254, 2
	global_load_dwordx4 v[6:9], v[4:5], off offset:3072
	global_load_dwordx4 v[10:13], v[34:35], off offset:3072
	global_load_dwordx4 v[14:17], v[4:5], off offset:2048
	global_load_dwordx4 v[18:21], v[34:35], off offset:2048
	global_load_dwordx4 v[22:25], v[4:5], off offset:1024
	global_load_dwordx4 v[26:29], v[34:35], off offset:1024
	global_load_dwordx4 v[30:33], v[4:5], off
	s_nop 0
	global_load_dwordx4 v[34:37], v[34:35], off
	v_readlane_b32 s2, v251, 44
	v_readlane_b32 s3, v251, 45
	s_waitcnt lgkmcnt(0)
	s_lshl_b32 s6, s0, 3
	v_readlane_b32 s0, v253, 4
	v_lshl_add_u64 v[4:5], s[2:3], 0, v[120:121]
	s_mov_b64 s[2:3], 0x2000
	v_lshl_add_u64 v[122:123], v[4:5], 0, s[2:3]
	v_lshlrev_b64 v[4:5], 11, v[150:151]
	s_add_i32 s0, s0, s6
	v_lshl_add_u64 v[126:127], s[88:89], 0, v[4:5]
	v_add_u32_e32 v4, s0, v54
	v_ashrrev_i32_e32 v5, 31, v4
	v_cmp_lt_i32_e32 vcc, v230, v231
	v_lshlrev_b64 v[54:55], 12, v[4:5]
	v_lshlrev_b64 v[4:5], 11, v[4:5]
	v_cndmask_b32_e32 v2, v229, v230, vcc
	v_lshl_add_u64 v[128:129], s[86:87], 0, v[54:55]
	v_lshlrev_b64 v[54:55], 12, v[150:151]
	v_lshl_add_u64 v[132:133], s[88:89], 0, v[4:5]
	v_mov_b32_e32 v4, v3
	v_mov_b32_e32 v5, v3
	v_readlane_b32 s10, v252, 32
	v_readlane_b32 s11, v252, 33
	v_readlane_b32 s12, v252, 34
	v_readlane_b32 s13, v252, 35
	v_lshlrev_b32_e32 v152, 2, v2
	s_ashr_i32 s7, s6, 31
	v_lshl_add_u64 v[130:131], s[86:87], 0, v[54:55]
	v_mov_b32_e32 v2, v3
	v_mov_b32_e32 v138, v3
	v_mov_b32_e32 v139, v3
	v_mov_b64_e32 v[56:57], v[4:5]
	v_mov_b64_e32 v[60:61], v[4:5]
	v_mov_b64_e32 v[64:65], v[4:5]
	v_mov_b64_e32 v[68:69], v[4:5]
	v_mov_b32_e32 v153, -1
	v_lshlrev_b64 v[124:125], 1, v[118:119]
	s_lshl_b64 s[8:9], s[6:7], 11
	s_lshl_b64 s[10:11], s[6:7], 12
	s_mov_b64 s[12:13], 0
	v_mov_b64_e32 v[144:145], v[138:139]
	v_mov_b64_e32 v[146:147], v[138:139]
	v_mov_b64_e32 v[148:149], v[138:139]
	v_mov_b64_e32 v[54:55], v[2:3]
	v_mov_b64_e32 v[58:59], v[2:3]
	v_mov_b64_e32 v[62:63], v[2:3]
	v_mov_b64_e32 v[66:67], v[2:3]
	v_readlane_b32 s14, v252, 36
	v_readlane_b32 s15, v252, 37
	v_readlane_b32 s16, v252, 38
	v_readlane_b32 s17, v252, 39
	v_readlane_b32 s22, v252, 44
	v_readlane_b32 s23, v252, 45
	s_waitcnt vmcnt(6)
	v_mov_b64_e32 v[88:89], v[12:13]
	v_mov_b64_e32 v[104:105], v[12:13]
	s_waitcnt vmcnt(4)
	v_mov_b64_e32 v[84:85], v[20:21]
	v_mov_b64_e32 v[96:97], v[20:21]
	s_waitcnt vmcnt(2)
	v_mov_b64_e32 v[72:73], v[28:29]
	v_mov_b64_e32 v[92:93], v[28:29]
	s_waitcnt vmcnt(0)
	v_mov_b64_e32 v[76:77], v[36:37]
	v_mov_b64_e32 v[80:81], v[36:37]
	v_mov_b64_e32 v[112:113], v[12:13]
	v_mov_b64_e32 v[116:117], v[20:21]
	v_mov_b64_e32 v[108:109], v[28:29]
	v_mov_b64_e32 v[100:101], v[36:37]
	v_mov_b64_e32 v[86:87], v[10:11]
	v_mov_b64_e32 v[82:83], v[18:19]
	v_mov_b64_e32 v[70:71], v[26:27]
	v_mov_b64_e32 v[74:75], v[34:35]
	v_mov_b64_e32 v[102:103], v[10:11]
	v_mov_b64_e32 v[94:95], v[18:19]
	v_mov_b64_e32 v[90:91], v[26:27]
	v_mov_b64_e32 v[78:79], v[34:35]
	v_mov_b64_e32 v[110:111], v[10:11]
	v_mov_b64_e32 v[114:115], v[18:19]
	v_mov_b64_e32 v[106:107], v[26:27]
	v_mov_b64_e32 v[98:99], v[34:35]
	s_branch .LBB0_275

.LBB0_280:
	s_and_b64 vcc, exec, s[2:3]
	s_cbranch_vccz .LBB0_297
	s_waitcnt vmcnt(0)
	v_mov_b32_e32 v10, v0
	v_readlane_b32 s2, v253, 28
	v_readlane_b32 s3, v253, 29
	v_and_b32_e32 v4, 0x1ff, v10
	s_andn2_b64 vcc, exec, s[2:3]
	v_readfirstlane_b32 s0, v4
	s_cbranch_vccnz .LBB0_297
	v_readlane_b32 s2, v251, 42
	v_readlane_b32 s3, v251, 43
	v_lshrrev_b32_e32 v2, 5, v10
	v_lshrrev_b32_e32 v6, 1, v10
	s_mov_b32 s4, s2
	s_ashr_i32 s5, s2, 31
	v_writelane_b32 v251, s2, 42
	v_and_b32_e32 v2, 4, v2
	v_bfe_u32 v5, v10, 2, 2
	v_and_b32_e32 v8, 24, v6
	v_writelane_b32 v251, s3, 43
	s_lshl_b64 s[2:3], s[4:5], 21
	v_readlane_b32 s4, v253, 18
	v_or3_b32 v2, v2, v5, v8
	v_lshrrev_b32_e32 v5, 3, v4
	v_lshlrev_b32_e32 v6, 4, v4
	v_and_b32_e32 v7, 32, v10
	s_add_u32 s18, s4, s2
	v_or_b32_e32 v11, 64, v5
	s_movk_i32 s4, 0x60
	v_bitop3_b32 v6, v6, v7, 48 bitop3:0x6c
	v_and_b32_e32 v7, 64, v10
	v_readlane_b32 s5, v253, 19
	v_and_or_b32 v9, v11, s4, v2
	v_or_b32_e32 v12, v6, v7
	s_addc_u32 s19, s5, s3
	s_lshr_b32 s2, s0, 6
	v_lshl_or_b32 v132, v9, 11, v12
	v_bfe_u32 v9, v10, 2, 4
	s_movk_i32 s4, 0x70
	s_lshr_b32 s3, s0, 8
	s_lshl_b32 s20, s2, 10
	v_and_or_b32 v11, v11, s4, v9
	v_readlane_b32 s4, v251, 30
	v_readlane_b32 s5, v251, 31
	s_add_u32 s14, s18, s4
	v_and_or_b32 v2, v5, 32, v2
	s_addc_u32 s15, s19, s5
	s_add_i32 s21, s20, 0x10000
	v_lshl_or_b32 v2, v2, 11, v12
	s_mov_b32 m0, s21
	s_add_i32 s22, s20, 0x12000
	v_lshl_or_b32 v134, v11, 11, v12
	v_and_or_b32 v11, v5, 48, v9
	global_load_lds_dwordx4 v2, s[14:15]
	s_mov_b32 m0, s22
	v_readlane_b32 s4, v251, 34
	v_lshl_or_b32 v136, v11, 11, v12
	global_load_lds_dwordx4 v132, s[14:15]
	s_mov_b32 m0, s20
	v_readlane_b32 s5, v251, 35
	s_add_i32 s23, s20, 0x2000
	s_nop 3
	global_load_lds_dwordx4 v136, s[4:5]
	s_mov_b32 m0, s23
	s_nop 0
	global_load_lds_dwordx4 v134, s[4:5]
	s_add_u32 s4, s14, 0x40000
	s_addc_u32 s5, s15, 0
	s_add_i32 s24, s20, 0x14000
	s_mov_b32 m0, s24
	s_add_i32 s25, s20, 0x16000
	global_load_lds_dwordx4 v2, s[4:5]
	s_mov_b32 m0, s25
	s_add_i32 s26, s20, 0x4000
	global_load_lds_dwordx4 v132, s[4:5]
	v_readlane_b32 s4, v251, 36
	s_mov_b32 m0, s26
	v_readlane_b32 s5, v251, 37
	s_add_i32 s27, s20, 0x6000
	s_cmp_lg_u32 s3, 1
	s_nop 2
	global_load_lds_dwordx4 v136, s[4:5]
	s_mov_b32 m0, s27
	s_nop 0
	global_load_lds_dwordx4 v134, s[4:5]
	v_readlane_b32 s4, v253, 2
	v_readlane_b32 s5, v253, 3
	v_readlane_b32 s28, v254, 2
	s_cbranch_scc1 .LBB0_284
	s_barrier

.LBB0_298:
	s_and_b64 vcc, exec, s[2:3]
	s_cbranch_vccz .LBB0_619
	s_cmp_gt_i32 s34, 1
	s_mov_b64 s[2:3], -1
	s_cbranch_scc0 .LBB0_582
	s_cmp_lt_i32 s34, 3
	s_cbranch_scc1 .LBB0_496
	s_cmp_gt_i32 s34, 3
	s_cbranch_scc0 .LBB0_306
	v_mov_b32_e32 v2, v0
	v_readlane_b32 s0, v253, 7
	v_and_b32_e32 v2, 0x1ff, v2
	s_nop 0
	v_or_b32_e32 v4, s0, v2
	s_mov_b32 s0, 0x40000
	v_cmp_gt_i32_e32 vcc, s0, v4
	s_and_saveexec_b64 s[2:3], vcc
	v_readlane_b32 s12, v253, 36
	v_readlane_b32 s14, v253, 38
	s_mov_b64 s[10:11], 0x4000
	v_readlane_b32 s13, v253, 37
	v_readlane_b32 s15, v253, 39
	s_mov_b32 s16, 0x2aaaaaab
	s_movk_i32 s17, 0x60
	s_cbranch_execz .LBB0_305
	v_readlane_b32 s4, v253, 2
	v_readlane_b32 s5, v253, 3
	v_readlane_b32 s4, v254, 2
	v_readlane_b32 s0, v251, 38
	s_waitcnt lgkmcnt(0)
	s_lshl_b32 s6, s4, 11
	v_lshl_add_u32 v5, v2, 2, s0
	s_lshl_b32 s0, s4, 9
	s_mov_b64 s[4:5], 0

.LBB0_500:
	s_cmp_eq_u32 s0, 0
	s_mov_b32 s19, s90
	s_cbranch_scc1 .LBB0_502
	v_readlane_b32 s2, v253, 2
	v_readlane_b32 s3, v253, 3
	v_readlane_b32 s2, v254, 2
	s_waitcnt lgkmcnt(0)
	v_cvt_f32_u32_e32 v2, s2
	s_sub_i32 s5, 0, s2
	s_lshr_b32 s4, s2, 1
	s_add_i32 s4, s4, s90
	v_rcp_iflag_f32_e32 v2, v2
	s_mul_i32 s3, s2, s0
	v_mul_f32_e32 v2, 0x4f7ffffe, v2
	v_cvt_u32_f32_e32 v2, v2
	s_nop 0
	v_readfirstlane_b32 s6, v2
	s_mul_i32 s5, s5, s6
	s_mul_hi_u32 s5, s6, s5
	s_add_i32 s6, s6, s5
	s_mul_hi_u32 s5, s4, s6
	s_mul_i32 s5, s5, s2
	s_sub_i32 s4, s4, s5
	s_sub_i32 s5, s4, s2
	s_cmp_ge_u32 s4, s2
	s_cselect_b32 s4, s5, s4
	s_sub_i32 s5, s4, s2
	s_cmp_ge_u32 s4, s2
	s_cselect_b32 s2, s5, s4
	s_add_i32 s19, s3, s2

.LBB0_586:
	s_waitcnt lgkmcnt(0)
	s_barrier
	ds_read2st64_b32 v[20:21], v117 offset1:4
	ds_read2st64_b32 v[22:23], v117 offset0:8 offset1:12
	ds_read2st64_b32 v[24:25], v117 offset0:16 offset1:20
	ds_read2st64_b32 v[26:27], v117 offset0:24 offset1:28
	s_mov_b32 s18, 0xffff0000
	s_ashr_i32 s21, s20, 31
	s_lshl_b64 s[16:17], s[20:21], 1
	s_waitcnt lgkmcnt(3)
	v_and_b32_e32 v2, 0xffff, v20
	v_lshl_or_b32 v16, v21, 16, v2
	s_waitcnt lgkmcnt(2)
	v_and_b32_e32 v2, 0xffff, v22
	v_lshl_or_b32 v17, v23, 16, v2
	s_waitcnt lgkmcnt(1)
	v_and_b32_e32 v2, 0xffff, v24
	v_lshl_or_b32 v18, v25, 16, v2
	s_waitcnt lgkmcnt(0)
	v_and_b32_e32 v2, 0xffff, v26
	v_lshl_or_b32 v19, v27, 16, v2
	v_lshrrev_b32_e32 v2, 16, v20
	v_and_or_b32 v20, v21, s18, v2
	v_lshrrev_b32_e32 v2, 16, v22
	v_and_or_b32 v21, v23, s18, v2
	v_lshrrev_b32_e32 v2, 16, v24
	v_and_or_b32 v22, v25, s18, v2
	v_lshl_add_u64 v[24:25], v[40:41], 0, s[16:17]
	v_lshrrev_b32_e32 v2, 16, v26
	global_store_dwordx4 v[24:25], v[16:19], off
	ds_read2st64_b32 v[24:25], v118 offset1:4
	v_and_or_b32 v23, v27, s18, v2
	v_lshl_add_u64 v[16:17], v[42:43], 0, s[16:17]
	global_store_dwordx4 v[16:17], v[20:23], off
	ds_read2st64_b32 v[22:23], v118 offset0:8 offset1:12
	ds_read2st64_b32 v[26:27], v118 offset0:16 offset1:20
	ds_read2st64_b32 v[28:29], v118 offset0:24 offset1:28
	s_waitcnt lgkmcnt(3)
	v_and_b32_e32 v2, 0xffff, v24
	v_lshl_or_b32 v16, v25, 16, v2
	s_waitcnt lgkmcnt(2)
	v_and_b32_e32 v2, 0xffff, v22
	v_lshl_or_b32 v17, v23, 16, v2
	s_waitcnt lgkmcnt(1)
	v_and_b32_e32 v2, 0xffff, v26
	v_lshl_or_b32 v18, v27, 16, v2
	s_waitcnt lgkmcnt(0)
	v_and_b32_e32 v2, 0xffff, v28
	v_lshl_or_b32 v19, v29, 16, v2
	v_lshrrev_b32_e32 v2, 16, v24
	v_and_or_b32 v20, v25, s18, v2
	v_lshrrev_b32_e32 v2, 16, v22
	v_and_or_b32 v21, v23, s18, v2
	v_lshrrev_b32_e32 v2, 16, v26
	v_lshl_add_u64 v[24:25], v[44:45], 0, s[16:17]
	v_and_or_b32 v22, v27, s18, v2
	v_lshrrev_b32_e32 v2, 16, v28
	global_store_dwordx4 v[24:25], v[16:19], off
	v_and_or_b32 v23, v29, s18, v2
	s_nop 0
	v_lshl_add_u64 v[16:17], v[46:47], 0, s[16:17]
	v_readlane_b32 s16, v253, 2
	v_readlane_b32 s17, v253, 3
	global_store_dwordx4 v[16:17], v[20:23], off
	s_barrier
	v_readlane_b32 s16, v254, 2
	s_waitcnt lgkmcnt(0)
	s_add_i32 s0, s16, s0
	s_cmpk_gt_i32 s0, 0x1ff
	s_cbranch_scc1 .LBB0_828

.LBB0_626:
	s_or_b64 exec, exec, s[2:3]
	s_and_saveexec_b64 s[8:9], vcc
	s_cbranch_execz .LBB0_633
	s_mov_b32 s7, s1
	v_readlane_b32 s12, v252, 30
	s_lshl_b64 s[2:3], s[6:7], 2
	v_readlane_b32 s26, v252, 44
	v_readlane_b32 s27, v252, 45
	s_add_u32 s2, s26, s2
	s_addc_u32 s3, s27, s3
	v_readlane_b32 s10, v253, 2
	v_lshlrev_b64 v[70:71], 2, v[38:39]
	v_readlane_b32 s11, v253, 3
	v_lshl_add_u64 v[4:5], s[2:3], 0, v[70:71]
	v_readlane_b32 s0, v254, 2
	global_load_dwordx4 v[22:25], v[4:5], off offset:3072
	global_load_dwordx4 v[26:29], v[4:5], off offset:2048
	global_load_dwordx4 v[30:33], v[4:5], off offset:1024
	global_load_dwordx4 v[34:37], v[4:5], off
	v_readlane_b32 s2, v253, 26
	v_cmp_lt_i32_e32 vcc, v230, v231
	v_readlane_b32 s3, v253, 27
	s_waitcnt lgkmcnt(0)
	s_lshl_b32 s10, s0, 3
	v_readlane_b32 s0, v253, 4
	s_add_i32 s0, s0, s10
	v_cndmask_b32_e32 v2, v229, v230, vcc
	v_add_u32_e32 v4, s0, v40
	v_ashrrev_i32_e32 v5, 31, v4
	v_lshlrev_b64 v[40:41], 12, v[4:5]
	v_lshlrev_b64 v[4:5], 11, v[4:5]
	v_lshl_add_u64 v[4:5], v[38:39], 1, v[4:5]
	v_lshl_add_u64 v[74:75], s[86:87], 0, v[40:41]
	v_lshlrev_b64 v[40:41], 12, v[84:85]
	v_lshl_add_u64 v[88:89], s[2:3], 0, v[4:5]
	v_mov_b32_e32 v4, v3
	v_mov_b32_e32 v5, v3
	v_readlane_b32 s13, v252, 31
	v_readlane_b32 s14, v252, 32
	v_readlane_b32 s15, v252, 33
	v_readlane_b32 s16, v252, 34
	v_readlane_b32 s17, v252, 35
	v_lshlrev_b32_e32 v98, 2, v2
	s_ashr_i32 s11, s10, 31
	v_lshl_add_u64 v[86:87], s[86:87], 0, v[40:41]
	v_mov_b32_e32 v2, v3
	v_mov_b32_e32 v90, v3
	v_mov_b32_e32 v91, v3
	v_mov_b64_e32 v[40:41], v[4:5]
	v_mov_b64_e32 v[44:45], v[4:5]
	v_mov_b64_e32 v[48:49], v[4:5]
	v_mov_b64_e32 v[52:53], v[4:5]
	v_lshl_add_u64 v[72:73], s[4:5], 0, v[70:71]
	v_mov_b32_e32 v99, -1
	s_lshl_b64 s[12:13], s[10:11], 12
	s_lshl_b64 s[14:15], s[10:11], 11
	s_mov_b64 s[16:17], 0
	v_mov_b64_e32 v[92:93], v[90:91]
	v_mov_b64_e32 v[94:95], v[90:91]
	v_mov_b64_e32 v[96:97], v[90:91]
	v_mov_b64_e32 v[38:39], v[2:3]
	v_mov_b64_e32 v[42:43], v[2:3]
	v_mov_b64_e32 v[46:47], v[2:3]
	v_mov_b64_e32 v[50:51], v[2:3]
	v_readlane_b32 s18, v252, 36
	v_readlane_b32 s19, v252, 37
	v_readlane_b32 s20, v252, 38
	v_readlane_b32 s21, v252, 39
	v_readlane_b32 s22, v252, 40
	v_readlane_b32 s23, v252, 41
	v_readlane_b32 s24, v252, 42
	v_readlane_b32 s25, v252, 43
	s_waitcnt vmcnt(3)
	v_mov_b64_e32 v[56:57], v[24:25]
	s_waitcnt vmcnt(2)
	v_mov_b64_e32 v[60:61], v[28:29]
	s_waitcnt vmcnt(1)
	v_mov_b64_e32 v[64:65], v[32:33]
	s_waitcnt vmcnt(0)
	v_mov_b64_e32 v[68:69], v[36:37]
	v_mov_b64_e32 v[54:55], v[22:23]
	v_mov_b64_e32 v[58:59], v[26:27]
	v_mov_b64_e32 v[62:63], v[30:31]
	v_mov_b64_e32 v[66:67], v[34:35]
	s_branch .LBB0_629

.LBB0_639:
	s_or_b64 exec, exec, s[2:3]
	s_and_saveexec_b64 s[8:9], vcc
	s_cbranch_execz .LBB0_826
	s_ashr_i32 s7, s6, 31
	v_readlane_b32 s12, v252, 30
	s_lshl_b64 s[2:3], s[6:7], 2
	v_readlane_b32 s26, v252, 44
	v_readlane_b32 s27, v252, 45
	s_add_u32 s2, s26, s2
	s_addc_u32 s3, s27, s3
	s_addk_i32 s6, 0x400
	v_lshlrev_b64 v[120:121], 2, v[118:119]
	s_ashr_i32 s7, s6, 31
	v_readlane_b32 s20, v252, 38
	v_lshl_add_u64 v[4:5], s[2:3], 0, v[120:121]
	s_lshl_b64 s[2:3], s[6:7], 2
	v_readlane_b32 s21, v252, 39
	s_add_u32 s2, s20, s2
	s_addc_u32 s3, s21, s3
	global_load_dwordx4 v[6:9], v[4:5], off offset:3072
	global_load_dwordx4 v[10:13], v[4:5], off offset:2048
	global_load_dwordx4 v[14:17], v[4:5], off offset:1024
	global_load_dwordx4 v[18:21], v[4:5], off
	v_lshl_add_u64 v[4:5], s[2:3], 0, v[120:121]
	global_load_dwordx4 v[22:25], v[4:5], off offset:3072
	global_load_dwordx4 v[26:29], v[4:5], off offset:2048
	global_load_dwordx4 v[30:33], v[4:5], off offset:1024
	global_load_dwordx4 v[34:37], v[4:5], off
	v_readlane_b32 s2, v251, 44
	v_lshl_add_u64 v[124:125], s[4:5], 0, v[120:121]
	v_readlane_b32 s3, v251, 45
	s_add_u32 s4, s2, 0x12000
	s_addc_u32 s5, s3, 0
	v_readlane_b32 s2, v253, 2
	v_readlane_b32 s3, v253, 3
	v_readlane_b32 s0, v254, 2
	v_cmp_lt_i32_e32 vcc, v230, v231
	v_lshlrev_b64 v[38:39], 11, v[148:149]
	v_lshlrev_b64 v[40:41], 12, v[148:149]
	v_cndmask_b32_e32 v42, v229, v230, vcc
	v_mov_b32_e32 v4, v3
	v_mov_b32_e32 v5, v3
	s_waitcnt lgkmcnt(0)
	s_lshl_b32 s10, s0, 3
	v_readlane_b32 s0, v253, 4
	v_mov_b32_e32 v2, v3
	v_lshlrev_b32_e32 v149, 2, v42
	v_lshl_add_u64 v[126:127], s[88:89], 0, v[38:39]
	v_lshl_add_u64 v[128:129], s[86:87], 0, v[40:41]
	v_mov_b64_e32 v[40:41], v[4:5]
	v_mov_b64_e32 v[44:45], v[4:5]
	v_mov_b64_e32 v[48:49], v[4:5]
	v_mov_b64_e32 v[52:53], v[4:5]
	s_add_i32 s0, s0, s10
	v_mov_b64_e32 v[38:39], v[2:3]
	v_mov_b64_e32 v[42:43], v[2:3]
	v_mov_b64_e32 v[46:47], v[2:3]
	v_mov_b64_e32 v[50:51], v[2:3]
	v_add_u32_e32 v4, s0, v70
	v_ashrrev_i32_e32 v5, 31, v4
	v_lshlrev_b64 v[70:71], 12, v[4:5]
	v_lshlrev_b64 v[72:73], 11, v[4:5]
	v_readlane_b32 s13, v252, 31
	v_readlane_b32 s14, v252, 32
	v_readlane_b32 s15, v252, 33
	v_mov_b32_e32 v130, v3
	v_mov_b32_e32 v131, v3
	s_ashr_i32 s11, s10, 31
	v_lshl_add_u64 v[4:5], s[86:87], 0, v[70:71]
	v_lshl_add_u64 v[138:139], s[88:89], 0, v[72:73]
	v_mov_b32_e32 v150, -1
	v_lshlrev_b64 v[122:123], 1, v[118:119]
	s_mov_b64 s[6:7], 0
	v_mov_b64_e32 v[132:133], v[130:131]
	v_mov_b64_e32 v[134:135], v[130:131]
	v_mov_b64_e32 v[136:137], v[130:131]
	s_lshl_b64 s[12:13], s[10:11], 11
	s_lshl_b64 s[14:15], s[10:11], 12
	v_readlane_b32 s16, v252, 34
	v_readlane_b32 s17, v252, 35
	v_readlane_b32 s18, v252, 36
	v_readlane_b32 s19, v252, 37
	v_readlane_b32 s22, v252, 40
	v_readlane_b32 s23, v252, 41
	v_readlane_b32 s24, v252, 42
	v_readlane_b32 s25, v252, 43
	s_waitcnt vmcnt(7)
	v_mov_b64_e32 v[84:85], v[8:9]
	s_waitcnt vmcnt(6)
	v_mov_b64_e32 v[80:81], v[12:13]
	s_waitcnt vmcnt(5)
	v_mov_b64_e32 v[76:77], v[16:17]
	s_waitcnt vmcnt(4)
	v_mov_b64_e32 v[72:73], v[20:21]
	v_mov_b64_e32 v[104:105], v[8:9]
	v_mov_b64_e32 v[92:93], v[12:13]
	v_mov_b64_e32 v[88:89], v[16:17]
	v_mov_b64_e32 v[108:109], v[20:21]
	v_mov_b64_e32 v[112:113], v[8:9]
	v_mov_b64_e32 v[116:117], v[12:13]
	v_mov_b64_e32 v[100:101], v[16:17]
	v_mov_b64_e32 v[96:97], v[20:21]
	v_mov_b64_e32 v[82:83], v[6:7]
	v_mov_b64_e32 v[78:79], v[10:11]
	v_mov_b64_e32 v[74:75], v[14:15]
	v_mov_b64_e32 v[70:71], v[18:19]
	v_mov_b64_e32 v[102:103], v[6:7]
	v_mov_b64_e32 v[90:91], v[10:11]
	v_mov_b64_e32 v[86:87], v[14:15]
	v_mov_b64_e32 v[106:107], v[18:19]
	v_mov_b64_e32 v[110:111], v[6:7]
	v_mov_b64_e32 v[114:115], v[10:11]
	v_mov_b64_e32 v[98:99], v[14:15]
	v_mov_b64_e32 v[94:95], v[18:19]
	s_branch .LBB0_642

.LBB0_648:
	v_readlane_b32 s2, v253, 2
	v_readlane_b32 s3, v253, 3
	s_waitcnt lgkmcnt(0)
	v_readlane_b32 s36, v254, 2
	s_waitcnt vmcnt(0)
	v_mov_b32_e32 v10, v0
	v_readlane_b32 s2, v253, 62
	v_readlane_b32 s3, v253, 63
	v_and_b32_e32 v4, 0x1ff, v10
	s_andn2_b64 vcc, exec, s[2:3]
	v_readfirstlane_b32 s0, v4
	s_cbranch_vccnz .LBB0_660
	v_readlane_b32 s2, v251, 42
	v_lshrrev_b32_e32 v2, 5, v10
	v_lshrrev_b32_e32 v6, 1, v10
	v_readlane_b32 s3, v251, 43
	s_mov_b32 s4, s2
	v_and_b32_e32 v2, 4, v2
	v_bfe_u32 v5, v10, 2, 2
	v_and_b32_e32 v8, 24, v6
	s_mul_i32 s3, s4, 0x480000
	v_readlane_b32 s4, v253, 24
	v_or3_b32 v2, v2, v5, v8
	v_lshrrev_b32_e32 v5, 3, v4
	v_lshlrev_b32_e32 v6, 4, v4
	v_and_b32_e32 v7, 32, v10
	s_add_u32 s18, s4, s3
	v_or_b32_e32 v11, 64, v5
	s_movk_i32 s4, 0x60
	v_bitop3_b32 v6, v6, v7, 48 bitop3:0x6c
	v_and_b32_e32 v7, 64, v10
	s_mul_hi_i32 s2, s2, 0x480000
	v_readlane_b32 s5, v253, 25
	v_and_or_b32 v9, v11, s4, v2
	v_or_b32_e32 v12, v6, v7
	s_addc_u32 s19, s5, s2
	s_lshr_b32 s2, s0, 6
	v_lshl_or_b32 v132, v9, 11, v12
	v_bfe_u32 v9, v10, 2, 4
	s_movk_i32 s4, 0x70
	s_lshr_b32 s3, s0, 8
	s_lshl_b32 s20, s2, 10
	v_and_or_b32 v11, v11, s4, v9
	v_readlane_b32 s4, v251, 3
	v_readlane_b32 s5, v251, 4
	s_add_u32 s14, s18, s4
	v_and_or_b32 v2, v5, 32, v2
	s_addc_u32 s15, s19, s5
	s_add_i32 s21, s20, 0x10000
	v_lshl_or_b32 v2, v2, 11, v12
	s_mov_b32 m0, s21
	s_add_i32 s22, s20, 0x12000
	v_lshl_or_b32 v134, v11, 11, v12
	v_and_or_b32 v11, v5, 48, v9
	global_load_lds_dwordx4 v2, s[14:15]
	s_mov_b32 m0, s22
	v_readlane_b32 s4, v251, 5
	v_lshl_or_b32 v136, v11, 11, v12
	global_load_lds_dwordx4 v132, s[14:15]
	s_mov_b32 m0, s20
	v_readlane_b32 s5, v251, 6
	s_add_i32 s23, s20, 0x2000
	s_nop 3
	global_load_lds_dwordx4 v136, s[4:5]
	s_mov_b32 m0, s23
	s_nop 0
	global_load_lds_dwordx4 v134, s[4:5]
	s_add_u32 s4, s14, 0x40000
	s_addc_u32 s5, s15, 0
	s_add_i32 s24, s20, 0x14000
	s_mov_b32 m0, s24
	s_add_i32 s25, s20, 0x16000
	global_load_lds_dwordx4 v2, s[4:5]
	s_mov_b32 m0, s25
	s_add_i32 s26, s20, 0x4000
	global_load_lds_dwordx4 v132, s[4:5]
	v_readlane_b32 s4, v251, 7
	s_mov_b32 m0, s26
	v_readlane_b32 s5, v251, 8
	s_add_i32 s27, s20, 0x6000
	s_cmp_lg_u32 s3, 1
	s_nop 2
	global_load_lds_dwordx4 v136, s[4:5]
	s_mov_b32 m0, s27
	s_nop 0
	global_load_lds_dwordx4 v134, s[4:5]
	s_cbranch_scc1 .LBB0_651
	s_barrier

.LBB0_1000:
	v_readlane_b32 s4, v253, 2
	v_readlane_b32 s5, v253, 3
	v_readlane_b32 s0, v254, 2
	s_waitcnt lgkmcnt(0)
	s_add_i32 s10, s0, s10
	s_cmpk_gt_i32 s10, 0x5cb
	s_cbranch_scc1 .LBB0_1310
